# acquire-side L1 invalidate (buffer_inv sc1) issued at barrier arrival by wave 1 of each workgroup (overlaps the wait; no cached loads between arrival and release); post-release invalidate kept only wh
# baseline (speedup 1.0000x reference)
; DI void xcd_barrier(const XcdBarrier& b) {
;     asm volatile("s_waitcnt vmcnt(0)" ::: "memory");
;     __syncthreads();
;     if (threadIdx.x == 0) {
;         unsigned* bar = b.bar;
;         __builtin_amdgcn_s_waitcnt(0);
;         unsigned nloc = b.st[0], nx = b.st[1];
;         if (nloc == 0u) { xcd_barrier_complete(bar, b.x, b.G, nloc, nx); b.st[0] = nloc; b.st[1] = nx; }
.LBB0_168:
	s_waitcnt vmcnt(0)
	s_barrier
	s_mov_b64 s[0:1], exec
	v_readlane_b32 s2, v235, 18
	v_readlane_b32 s3, v235, 19
	s_and_b64 s[2:3], s[0:1], s[2:3]
	s_mov_b64 exec, s[2:3]
	s_cbranch_execnz .Lxg_t0_1
	s_mov_b64 exec, s[0:1]
	v_cmp_eq_u32_e64 s[2:3], 64, v176
	s_cmp_eq_u64 s[2:3], 0
	s_cbranch_scc1 .LBB0_213
	buffer_inv sc1
	s_waitcnt vmcnt(0)
	s_branch .LBB0_213
.Lxg_t0_1:
	v_readlane_b32 s2, v235, 22
	s_waitcnt vmcnt(0) expcnt(0) lgkmcnt(0)
	s_nop 0
	v_mov_b32_e32 v0, s2
	ds_read_b32 v2, v0
	ds_read_b32 v1, v0 offset:4
	s_waitcnt lgkmcnt(1)
	v_cmp_ne_u32_e32 vcc, 0, v2
	s_cbranch_vccnz .LBB0_182
	s_mov_b32 s8, 1
	s_branch .LBB0_172

; DI void xcd_barrier(const XcdBarrier& b) {
;     asm volatile("s_waitcnt vmcnt(0)" ::: "memory");
;     __syncthreads();
;     if (threadIdx.x == 0) {
;         unsigned* bar = b.bar;
;         __builtin_amdgcn_s_waitcnt(0);
;         unsigned nloc = b.st[0], nx = b.st[1];
;         if (nloc == 0u) { xcd_barrier_complete(bar, b.x, b.G, nloc, nx); b.st[0] = nloc; b.st[1] = nx; }
; __global__ void __launch_bounds__(256, 2) hybrid_megakernel(Params p) {
;     ...
;     for (int vb = bid; vb < 512; vb += nb)
;       for (int j = vb >> 3; j < 128; j += 64) resid_rows<4>(p, l, (vb & 7) * 2048 + j * 16 + wid * 4, xin);
;     if (l < 3) xcd_barrier(xg);
.LBB0_632:
	v_readlane_b32 s0, v234, 24
	s_cmp_lg_u32 s0, 3
	s_cbranch_scc0 .LBB0_160
	s_waitcnt vmcnt(0)
	s_waitcnt lgkmcnt(0)
	s_barrier
	s_mov_b64 s[0:1], exec
	v_readlane_b32 s2, v235, 18
	v_readlane_b32 s3, v235, 19
	s_and_b64 s[2:3], s[0:1], s[2:3]
	s_mov_b64 exec, s[2:3]
	s_cbranch_execnz .Lxg_t0_5
	s_mov_b64 exec, s[0:1]
	v_cmp_eq_u32_e64 s[2:3], 64, v176
	s_cmp_eq_u64 s[2:3], 0
	s_cbranch_scc1 .LBB0_159
	buffer_inv sc1
	s_waitcnt vmcnt(0)
	s_branch .LBB0_159
